# ragged-round overlap, rebalance variant: workgroups 0..63 run 4 P2 items, every other workgroup 8 (drop 3)
# baseline (speedup 1.0000x reference)
; __global__ void __launch_bounds__(512, 2) hybrid_fwd(Args a) {
;     ...
;         for (int i0 = bx; i0 < N_A + N_B; i0 += G) {
;             int it = i0;
;             if (xmap) { const int k = i0 / G;
;                 if (i0 < N_A) it = xcd * (N_A / 8) + k * perx + jx;
;                 else { const int kb = (i0 - N_A) / G; it = N_A + xcd * (N_B / 8) + kb * perx + jx; } }
.LBB0_303:
	s_or_b64 exec, exec, s[14:15]
	s_add_i32 s22, s22, s92
	s_cmp_eq_u32 s101, 1
	s_cbranch_scc0 .Lp2_latch_orig
	s_cmp_lt_u32 s2, 64
	s_cbranch_scc0 .Lp2_notlate
	s_cmpk_lt_i32 s22, 0x400
	s_cbranch_scc1 .LBB0_304
	s_branch .LBB0_339
.Lp2_notlate:
	s_cmpk_lt_i32 s22, 0x700
	s_cbranch_scc1 .LBB0_304
	s_cmp_lt_u32 s2, 0x100
	s_cbranch_scc0 .LBB0_339
	s_cmp_lt_u32 s22, 0x1000
	s_cbranch_scc0 .LBB0_339
	s_mov_b32 s22, 0x1000
	s_branch .LBB0_304

; __global__ void __launch_bounds__(512, 2) hybrid_fwd(Args a) {
;     ...
;         for (int i0 = bx; i0 < N_A + N_B; i0 += G) {
;             int it = i0;
;             if (xmap) { const int k = i0 / G;
;                 if (i0 < N_A) it = xcd * (N_A / 8) + k * perx + jx;
;                 else { const int kb = (i0 - N_A) / G; it = N_A + xcd * (N_B / 8) + kb * perx + jx; } }
.LBB0_309:
	v_readlane_b32 s16, v242, 9
	s_add_i32 s16, s23, s16
	s_nop 0
	v_mov_b32_e32 v1, s16
	s_cmp_lt_u32 s22, 0x1000
	s_cbranch_scc1 .Lp2_noextra
	s_sub_u32 s16, s2, 64
	s_lshr_b32 s17, s16, 6
	s_add_u32 s17, s17, 3
	s_lshl_b32 s17, s17, 5
	s_and_b32 s16, s16, 63
	s_lshr_b32 s16, s16, 3
	s_add_u32 s16, s16, s17
	s_and_b32 s17, s2, 7
	s_mul_i32 s17, s17, 0xc0
	s_add_u32 s16, s16, s17
	s_add_u32 s16, s16, 0x100
	v_mov_b32_e32 v1, s16
